# stack B + selected-loop block ids carried in SGPRs (no LDS re-read at loop head) and tail block-id reads issued early
# speedup vs baseline: 1.0509x; 1.0155x over previous
.LBB0_1038:
	s_or_b64 exec, exec, s[0:1]
	s_bcnt1_i32_b32 s0, s21
	s_bcnt1_i32_b32 s1, s22
	s_bcnt1_i32_b32 s21, s23
	s_lshl_b32 s22, s40, 25
	s_add_u32 s22, s36, s22
	s_addc_u32 s23, s37, 0
	s_bcnt1_i32_b32 s20, s20
	s_add_i32 s0, s0, s20
	s_add_i32 s79, s0, s1
	s_add_i32 s79, s79, s21
	s_lshl_b32 s0, s29, 7
	s_add_u32 s24, s22, s0
	v_sub_co_u32_e64 v32, s[0:1], s79, 1
	s_waitcnt lgkmcnt(0)
	s_barrier
	s_nop 0
	v_cndmask_b32_e64 v0, 0, -1, s[0:1]
	v_lshlrev_b32_e32 v0, 2, v0
	v_add_u32_e32 v0, s72, v0
	ds_read_b32 v0, v0
	s_addc_u32 s25, s23, 0
	s_lshl_b32 s0, s47, 20
	s_add_u32 s20, s55, s0
	s_addc_u32 s21, s56, 0
	s_waitcnt lgkmcnt(0)
	v_readfirstlane_b32 s0, v0
	s_mov_b32 s32, s0
	s_lshl_b32 s0, s0, 6
	s_ashr_i32 s1, s0, 31
	s_lshl_b64 s[22:23], s[0:1], 12
	s_add_u32 s22, s24, s22
	s_addc_u32 s23, s25, s23
	s_lshl_b64 s[0:1], s[0:1], 1
	s_add_u32 s0, s20, s0
	s_addc_u32 s1, s21, s1
	s_cmp_lt_u32 s79, 2
	v_mov_b32_e32 v139, v123
	v_mov_b32_e32 v141, v123
	s_cselect_b64 vcc, -1, 0
	v_lshl_add_u64 v[0:1], s[22:23], 0, v[138:139]
	v_lshl_add_u64 v[2:3], s[0:1], 0, v[140:141]
	v_cndmask_b32_e32 v8, 1, v32, vcc
	v_lshl_add_u64 v[0:1], v[0:1], 0, v[122:123]
	v_lshl_add_u64 v[4:5], v[2:3], 0, v[122:123]
	v_lshlrev_b32_e32 v8, 2, v8
	global_load_dwordx4 v[0:3], v[0:1], off offset:2560
	s_nop 0
	global_load_dwordx4 v[4:7], v[4:5], off
	v_add_u32_e32 v8, s72, v8
	ds_read_b32 v8, v8
	v_readfirstlane_b32 s80, v32
	v_add_f32_e32 v137, v146, v146
	v_mul_f32_e32 v188, 0x40400000, v146
	v_mul_f32_e32 v189, 0x41800000, v146
	s_waitcnt lgkmcnt(0)
	v_readfirstlane_b32 s0, v8
	s_mov_b32 s97, s0
	s_lshl_b32 s0, s0, 6
	s_ashr_i32 s1, s0, 31
	s_lshl_b64 s[22:23], s[0:1], 12
	s_add_u32 s22, s24, s22
	s_addc_u32 s23, s25, s23
	s_lshl_b64 s[0:1], s[0:1], 1
	s_add_u32 s0, s20, s0
	s_addc_u32 s1, s21, s1
	v_lshl_add_u64 v[8:9], s[22:23], 0, v[138:139]
	v_lshl_add_u64 v[10:11], s[0:1], 0, v[140:141]
	v_lshl_add_u64 v[8:9], v[8:9], 0, v[122:123]
	v_lshl_add_u64 v[12:13], v[10:11], 0, v[122:123]
	global_load_dwordx4 v[8:11], v[8:9], off offset:2560
	s_nop 0
	global_load_dwordx4 v[12:15], v[12:13], off
	s_cmp_lt_u32 s79, 3
	s_cselect_b64 s[0:1], -1, 0
	v_cndmask_b32_e64 v16, 2, v32, s[0:1]
	v_lshlrev_b32_e32 v16, 2, v16
	v_add_u32_e32 v16, s72, v16
	v_mul_f32_e32 v190, 0x42000000, v146
	v_mul_f32_e32 v191, 0x42400000, v146
	v_mul_f32_e32 v192, 0, v146
	s_waitcnt vmcnt(3)
	ds_write_b128 v151, v[0:3]
	s_waitcnt vmcnt(2)
	ds_write2_b64 v187, v[4:5], v[6:7] offset1:2
	s_waitcnt vmcnt(1)
	ds_write_b128 v151, v[8:11] offset:10240
	s_waitcnt vmcnt(0)
	ds_write2_b64 v186, v[12:13], v[14:15] offset1:2
	s_lshl_b32 s98, s47, 20
	s_add_u32 s98, s57, s98
	s_addc_u32 s99, s60, 0
	s_add_i32 s29, s74, 0xfffffe01
	s_andn2_b32 s29, s29, 63
	s_cmp_gt_i32 s75, 31
	s_cselect_b32 s29, s29, 0
	s_sub_i32 s30, s74, s29
	s_ashr_i32 s30, s30, 6
	v_mov_b32_e32 v4, v138
	v_mov_b32_e32 v5, 0
	v_mov_b32_e32 v6, v140
	v_mov_b32_e32 v7, 0
	s_min_i32 s22, s30, 0
	s_lshl_b32 s22, s22, 6
	s_add_i32 s22, s22, s29
	s_ashr_i32 s23, s22, 31
	s_lshl_b64 s[100:101], s[22:23], 12
	s_add_u32 s100, s24, s100
	s_addc_u32 s101, s25, s101
	s_lshl_b64 s[22:23], s[22:23], 1
	s_add_u32 s22, s98, s22
	s_addc_u32 s23, s99, s23
	v_lshl_add_u64 v[0:1], s[100:101], 0, v[4:5]
	v_lshl_add_u64 v[2:3], s[22:23], 0, v[6:7]
	v_lshl_add_u64 v[0:1], v[0:1], 0, v[122:123]
	v_lshl_add_u64 v[2:3], v[2:3], 0, v[122:123]
	global_load_dwordx4 v[240:243], v[0:1], off offset:3072
	global_load_dwordx4 v[244:247], v[2:3], off
	s_min_i32 s22, s30, 1
	s_lshl_b32 s22, s22, 6
	s_add_i32 s22, s22, s29
	s_ashr_i32 s23, s22, 31
	s_lshl_b64 s[100:101], s[22:23], 12
	s_add_u32 s100, s24, s100
	s_addc_u32 s101, s25, s101
	s_lshl_b64 s[22:23], s[22:23], 1
	s_add_u32 s22, s98, s22
	s_addc_u32 s23, s99, s23
	v_lshl_add_u64 v[0:1], s[100:101], 0, v[4:5]
	v_lshl_add_u64 v[2:3], s[22:23], 0, v[6:7]
	v_lshl_add_u64 v[0:1], v[0:1], 0, v[122:123]
	v_lshl_add_u64 v[2:3], v[2:3], 0, v[122:123]
	global_load_dwordx4 v[248:251], v[0:1], off offset:3072
	global_load_dwordx4 v[252:255], v[2:3], off
	ds_read_b32 v0, v16
	s_waitcnt lgkmcnt(0)
	v_readfirstlane_b32 s0, v0
	s_mov_b32 s89, s0
	s_lshl_b32 s0, s0, 6
	s_ashr_i32 s1, s0, 31
	s_lshl_b64 s[22:23], s[0:1], 12
	s_add_u32 s22, s24, s22
	s_addc_u32 s23, s25, s23
	s_lshl_b64 s[0:1], s[0:1], 1
	s_add_u32 s0, s20, s0
	s_addc_u32 s1, s21, s1
	s_cmp_lt_u32 s79, 4
	v_lshl_add_u64 v[0:1], s[22:23], 0, v[138:139]
	v_lshl_add_u64 v[2:3], s[0:1], 0, v[140:141]
	s_cselect_b64 s[0:1], -1, 0
	v_lshl_add_u64 v[0:1], v[0:1], 0, v[122:123]
	v_cndmask_b32_e64 v4, 3, v32, s[0:1]
	v_lshl_add_u64 v[2:3], v[2:3], 0, v[122:123]
	global_load_dwordx4 v[20:23], v[0:1], off offset:2560
	global_load_dwordx4 v[16:19], v[2:3], off
	v_lshlrev_b32_e32 v0, 2, v4
	v_add_u32_e32 v0, s72, v0
	ds_read_b32 v0, v0
	s_waitcnt lgkmcnt(0)
	v_readfirstlane_b32 s0, v0
	s_mov_b32 s91, s0
	s_lshl_b32 s0, s0, 6
	s_ashr_i32 s1, s0, 31
	s_lshl_b64 s[22:23], s[0:1], 12
	s_add_u32 s22, s24, s22
	s_addc_u32 s23, s25, s23
	s_lshl_b64 s[0:1], s[0:1], 1
	s_add_u32 s0, s20, s0
	v_lshl_add_u64 v[0:1], s[22:23], 0, v[138:139]
	s_addc_u32 s1, s21, s1
	v_lshl_add_u64 v[0:1], v[0:1], 0, v[122:123]
	v_lshl_add_u64 v[2:3], s[0:1], 0, v[140:141]
	v_lshl_add_u64 v[2:3], v[2:3], 0, v[122:123]
	global_load_dwordx4 v[28:31], v[0:1], off offset:2560
	global_load_dwordx4 v[24:27], v[2:3], off
	s_waitcnt lgkmcnt(0)
	s_barrier
	v_lshl_add_u64 v[0:1], s[24:25], 0, v[138:139]
	v_lshl_add_u64 v[120:121], v[0:1], 0, v[122:123]
	s_and_b64 vcc, exec, vcc
	s_cbranch_vccnz .LBB0_1050
	v_lshl_add_u64 v[0:1], s[20:21], 0, v[140:141]
	v_mov_b32_e32 v36, 0
	v_lshl_add_u64 v[148:149], v[0:1], 0, v[122:123]
	v_sub_u32_e32 v139, v144, v124
	v_mov_b32_e32 v32, v123
	v_mov_b32_e32 v33, v123
	v_mov_b32_e32 v34, v123
	v_mov_b32_e32 v35, v123
	s_mov_b32 s83, 5
	s_movk_i32 s81, 0x80
	s_mov_b32 s82, s72
	v_mov_b32_e32 v37, v36
	v_mov_b32_e32 v38, v36
	v_mov_b32_e32 v39, v36
	v_mov_b32_e32 v40, v36
	v_mov_b32_e32 v41, v36
	v_mov_b32_e32 v42, v36
	v_mov_b32_e32 v43, v36
	v_mov_b32_e32 v44, v36
	v_mov_b32_e32 v45, v36
	v_mov_b32_e32 v46, v36
	v_mov_b32_e32 v47, v36
	v_mov_b32_e32 v84, v36
	v_mov_b32_e32 v85, v36
	v_mov_b32_e32 v86, v36
	v_mov_b32_e32 v87, v36
.LBB0_1040:
	s_mov_b32 s22, s32
	s_ashr_i32 s23, s22, 5
	s_cmp_eq_u32 s23, 2
	s_cselect_b32 s0, s77, s78
	s_cmp_eq_u32 s23, 1
	s_cselect_b32 s0, s27, s0
	s_cmp_lt_u32 s22, 32
	s_cselect_b32 s0, s26, s0
	s_lshl_b32 s29, 1, s22
	s_and_b32 s20, s0, s29
	s_mov_b64 s[0:1], -1
	s_cmp_lg_u32 s20, 0
	s_mov_b64 s[20:21], -1
	s_cbranch_scc1 .LBB0_1042
	v_lshl_add_u32 v0, s23, 2, v160
	ds_read_b32 v0, v0
	s_waitcnt lgkmcnt(0)
	v_and_b32_e32 v0, s29, v0
	v_cmp_ne_u32_e32 vcc, 0, v0
	s_orn2_b64 s[20:21], vcc, exec
.LBB0_1042:
	s_mov_b32 s23, s97
	s_ashr_i32 s29, s23, 5
	s_cmp_eq_u32 s29, 2
	s_cselect_b32 s30, s77, s78
	s_cmp_eq_u32 s29, 1
	s_cselect_b32 s30, s27, s30
	s_cmp_lt_u32 s23, 32
	s_cselect_b32 s31, s26, s30
	s_lshl_b32 s30, 1, s23
	s_and_b32 s31, s31, s30
	s_cmp_lg_u32 s31, 0
	s_cbranch_scc1 .LBB0_1044
	v_lshl_add_u32 v0, s29, 2, v160
	ds_read_b32 v0, v0
	s_waitcnt lgkmcnt(0)
	v_and_b32_e32 v0, s30, v0
	v_cmp_ne_u32_e32 vcc, 0, v0
	s_orn2_b64 s[0:1], vcc, exec

.LBB0_1048:
	s_setprio 0
	s_add_i32 s0, s83, -1
	s_cmp_lt_u32 s0, s79
	s_cselect_b32 s0, s0, s80
	s_lshl_b32 s0, s0, 2
	s_add_i32 s0, s0, 0x24900
	v_mov_b32_e32 v33, s0
	ds_read_b32 v33, v33
	s_cmp_lt_u32 s83, s79
	s_cselect_b32 s0, s83, s80
	s_lshl_b32 s0, s0, 2
	s_add_i32 s0, s0, 0x24900
	v_mov_b32_e32 v34, s0
	ds_read_b32 v34, v34
	s_and_b32 s0, s81, 0x80
	s_mulk_i32 s0, 0xa0
	v_add_u32_e32 v32, s0, v151
	s_waitcnt vmcnt(3)
	ds_write_b128 v32, v[20:23]
	v_add_u32_e32 v20, s0, v152
	s_add_i32 s0, s81, 64
	s_and_b32 s0, s0, 0xc0
	v_add_u32_e32 v20, 0xa000, v20
	s_mulk_i32 s0, 0xa0
	s_waitcnt vmcnt(2)
	ds_write2_b64 v20, v[16:17], v[18:19] offset1:2
	v_add_u32_e32 v16, s0, v151
	s_waitcnt vmcnt(1)
	ds_write_b128 v16, v[28:31]
	v_add_u32_e32 v16, s0, v152
	s_add_i32 s0, s83, -1
	s_cmp_lt_u32 s0, s79
	s_cselect_b32 s0, s0, s80
	s_lshl_b32 s0, s0, 2
	s_add_i32 s22, 0, 0x24900
	v_add_u32_e32 v16, 0xa000, v16
	s_add_i32 s0, s22, s0
	s_waitcnt vmcnt(0)
	ds_write2_b64 v16, v[24:25], v[26:27] offset1:2
	s_waitcnt lgkmcnt(4)
	v_readfirstlane_b32 s98, v33
	v_readfirstlane_b32 s99, v34
	s_mov_b32 s0, s98
	s_lshl_b32 s0, s0, 6
	s_ashr_i32 s1, s0, 31
	s_lshl_b64 s[20:21], s[0:1], 12
	s_cmp_lt_u32 s83, s79
	v_lshl_add_u64 v[18:19], s[0:1], 1, v[148:149]
	s_cselect_b32 s0, s83, s80
	s_lshl_b32 s0, s0, 2
	v_lshl_add_u64 v[16:17], v[120:121], 0, s[20:21]
	s_add_i32 s0, s22, s0
	global_load_dwordx4 v[20:23], v[16:17], off offset:2560
	s_nop 0
	global_load_dwordx4 v[16:19], v[18:19], off
	s_addk_i32 s81, 0x80
	s_add_i32 s82, s82, 8
	s_mov_b32 s0, s99
	s_lshl_b32 s0, s0, 6
	s_ashr_i32 s1, s0, 31
	s_lshl_b64 s[20:21], s[0:1], 12
	v_lshl_add_u64 v[24:25], v[120:121], 0, s[20:21]
	v_lshl_add_u64 v[26:27], s[0:1], 1, v[148:149]
	global_load_dwordx4 v[28:31], v[24:25], off offset:2560
	s_nop 0
	global_load_dwordx4 v[24:27], v[26:27], off
	s_waitcnt lgkmcnt(0)
	s_barrier
	s_mov_b32 s32, s89
	s_mov_b32 s97, s91
	s_mov_b32 s89, s98
	s_mov_b32 s91, s99
	s_add_i32 s0, s83, 2
	s_add_i32 s1, s83, -2
	s_cmp_lt_u32 s1, s79
	s_cbranch_scc0 .LBB0_1051
	v_mov_b64_e32 v[32:33], v[80:81]
	s_mov_b32 s83, s0
	v_mov_b64_e32 v[34:35], v[82:83]
	v_mov_b32_e32 v36, v0
	v_mov_b32_e32 v37, v1
	v_mov_b32_e32 v38, v2
	v_mov_b32_e32 v39, v3
	v_mov_b32_e32 v40, v4
	v_mov_b32_e32 v41, v5
	v_mov_b32_e32 v42, v6
	v_mov_b32_e32 v43, v7
	v_mov_b32_e32 v44, v8
	v_mov_b32_e32 v45, v9
	v_mov_b32_e32 v46, v10
	v_mov_b32_e32 v47, v11
	v_mov_b32_e32 v84, v12
	v_mov_b32_e32 v85, v13
	v_mov_b32_e32 v86, v14
	v_mov_b32_e32 v87, v15
	s_branch .LBB0_1040
